# union-3: union-2 plus MMA segments restructured (setprio before the pre-MMA barrier, post-MMA barrier signalled 2 MFMAs early with trailing MFMAs at prio 3)
# speedup vs baseline: 1.0104x; 1.0003x over previous
.LBB0_182:
	s_add_u32 s57, s22, 0x100
	s_addc_u32 s59, s23, 0
	s_add_u32 s22, s24, 0x80
	v_mov_b32_e32 v0, 0
	s_addc_u32 s23, s25, 0
	s_mov_b32 s24, 0
	v_mov_b32_e32 v1, v0
	v_mov_b32_e32 v2, v0
	v_mov_b32_e32 v3, v0
	v_mov_b32_e32 v4, v0
	v_mov_b32_e32 v5, v0
	v_mov_b32_e32 v6, v0
	v_mov_b32_e32 v7, v0
	v_mov_b32_e32 v8, v0
	v_mov_b32_e32 v9, v0
	v_mov_b32_e32 v10, v0
	v_mov_b32_e32 v11, v0
	v_mov_b32_e32 v16, v0
	v_mov_b32_e32 v17, v0
	v_mov_b32_e32 v18, v0
	v_mov_b32_e32 v19, v0
	v_mov_b32_e32 v24, v0
	v_mov_b32_e32 v25, v0
	v_mov_b32_e32 v26, v0
	v_mov_b32_e32 v27, v0
	v_mov_b32_e32 v32, v0
	v_mov_b32_e32 v33, v0
	v_mov_b32_e32 v34, v0
	v_mov_b32_e32 v35, v0
	v_mov_b32_e32 v48, v0
	v_mov_b32_e32 v49, v0
	v_mov_b32_e32 v50, v0
	v_mov_b32_e32 v51, v0
	v_mov_b32_e32 v52, v0
	v_mov_b32_e32 v53, v0
	v_mov_b32_e32 v54, v0
	v_mov_b32_e32 v55, v0
	v_mov_b32_e32 v12, v0
	v_mov_b32_e32 v13, v0
	v_mov_b32_e32 v14, v0
	v_mov_b32_e32 v15, v0
	v_mov_b32_e32 v20, v0
	v_mov_b32_e32 v21, v0
	v_mov_b32_e32 v22, v0
	v_mov_b32_e32 v23, v0
	v_mov_b32_e32 v28, v0
	v_mov_b32_e32 v29, v0
	v_mov_b32_e32 v30, v0
	v_mov_b32_e32 v31, v0
	v_mov_b32_e32 v36, v0
	v_mov_b32_e32 v37, v0
	v_mov_b32_e32 v38, v0
	v_mov_b32_e32 v39, v0
	v_mov_b32_e32 v40, v0
	v_mov_b32_e32 v41, v0
	v_mov_b32_e32 v42, v0
	v_mov_b32_e32 v43, v0
	v_mov_b32_e32 v44, v0
	v_mov_b32_e32 v45, v0
	v_mov_b32_e32 v46, v0
	v_mov_b32_e32 v47, v0
	v_mov_b32_e32 v56, v0
	v_mov_b32_e32 v57, v0
	v_mov_b32_e32 v58, v0
	v_mov_b32_e32 v59, v0
	v_mov_b32_e32 v60, v0
	v_mov_b32_e32 v61, v0
	v_mov_b32_e32 v62, v0
	v_mov_b32_e32 v63, v0
	v_mov_b32_e32 v64, v0
	v_mov_b32_e32 v65, v0
	v_mov_b32_e32 v66, v0
	v_mov_b32_e32 v67, v0
	v_mov_b32_e32 v68, v0
	v_mov_b32_e32 v69, v0
	v_mov_b32_e32 v70, v0
	v_mov_b32_e32 v71, v0
	v_mov_b32_e32 v72, v0
	v_mov_b32_e32 v73, v0
	v_mov_b32_e32 v74, v0
	v_mov_b32_e32 v75, v0
	v_mov_b32_e32 v84, v0
	v_mov_b32_e32 v85, v0
	v_mov_b32_e32 v86, v0
	v_mov_b32_e32 v87, v0
	v_mov_b32_e32 v96, v0
	v_mov_b32_e32 v97, v0
	v_mov_b32_e32 v98, v0
	v_mov_b32_e32 v99, v0
	v_mov_b32_e32 v100, v0
	v_mov_b32_e32 v101, v0
	v_mov_b32_e32 v102, v0
	v_mov_b32_e32 v103, v0
	v_mov_b32_e32 v128, v0
	v_mov_b32_e32 v129, v0
	v_mov_b32_e32 v130, v0
	v_mov_b32_e32 v131, v0
	v_mov_b32_e32 v132, v0
	v_mov_b32_e32 v133, v0
	v_mov_b32_e32 v134, v0
	v_mov_b32_e32 v135, v0
	v_mov_b32_e32 v76, v0
	v_mov_b32_e32 v77, v0
	v_mov_b32_e32 v78, v0
	v_mov_b32_e32 v79, v0
	v_mov_b32_e32 v80, v0
	v_mov_b32_e32 v81, v0
	v_mov_b32_e32 v82, v0
	v_mov_b32_e32 v83, v0
	v_mov_b32_e32 v88, v0
	v_mov_b32_e32 v89, v0
	v_mov_b32_e32 v90, v0
	v_mov_b32_e32 v91, v0
	v_mov_b32_e32 v92, v0
	v_mov_b32_e32 v93, v0
	v_mov_b32_e32 v94, v0
	v_mov_b32_e32 v95, v0
	v_mov_b32_e32 v120, v0
	v_mov_b32_e32 v121, v0
	v_mov_b32_e32 v122, v0
	v_mov_b32_e32 v123, v0
	v_mov_b32_e32 v124, v0
	v_mov_b32_e32 v125, v0
	v_mov_b32_e32 v126, v0
	v_mov_b32_e32 v127, v0
	v_mov_b32_e32 v136, v0
	v_mov_b32_e32 v137, v0
	v_mov_b32_e32 v138, v0
	v_mov_b32_e32 v139, v0
	v_mov_b32_e32 v140, v0
	v_mov_b32_e32 v141, v0
	v_mov_b32_e32 v142, v0
	v_mov_b32_e32 v143, v0
	v_readlane_b32 s2, v246, 43
	s_cmp_eq_u32 s2, 0
	s_cbranch_scc1 .LBB0_183
	s_add_i32 s60, s24, 2
	s_add_u32 s2, s22, 0x80
	s_addc_u32 s3, s23, 0
	s_add_i32 s61, 0, 0x10000
	s_cmp_eq_u32 s51, s24
	s_cselect_b32 s25, s1, s3
	s_cselect_b32 s24, s0, s2
	s_cselect_b32 s3, s21, s59
	s_cselect_b32 s2, s20, s57
	s_add_i32 s62, 0, 0x14000
	v_add_u32_e32 v116, s61, v192
	v_add_u32_e32 v156, s62, v192
	ds_read_b128 v[104:107], v116
	ds_read_b128 v[108:111], v116 offset:1024
	ds_read_b128 v[112:115], v116 offset:2048
	ds_read_b128 v[116:119], v116 offset:3072
	ds_read_b128 v[144:147], v156
	ds_read_b128 v[148:151], v156 offset:1024
	ds_read_b128 v[152:155], v156 offset:2048
	ds_read_b128 v[156:159], v156 offset:3072
	v_lshl_add_u64 v[190:191], s[22:23], 0, v[188:189]
	s_add_i32 m0, s31, 0xc000
	ds_read_b128 v[160:163], v194
	ds_read_b128 v[164:167], v194 offset:1024
	ds_read_b128 v[196:199], v194 offset:2048
	ds_read_b128 v[200:203], v194 offset:3072
	ds_read_b128 v[210:213], v194 offset:4096
	ds_read_b128 v[214:217], v194 offset:5120
	ds_read_b128 v[218:221], v194 offset:6144
	ds_read_b128 v[222:225], v194 offset:7168
	global_load_lds_dwordx4 v[190:191], off
	v_lshl_add_u64 v[190:191], s[22:23], 0, v[186:187]
	s_add_i32 m0, s31, 0xe000
	s_nop 0
	global_load_lds_dwordx4 v[190:191], off
	s_waitcnt vmcnt(40)
	s_waitcnt lgkmcnt(0)
	s_setprio 1
	s_barrier
	v_mfma_f32_16x16x32_bf16 v[140:143], v[104:107], v[160:163], v[140:143]
	v_mfma_f32_16x16x32_bf16 v[140:143], v[108:111], v[164:167], v[140:143]
	v_mfma_f32_16x16x32_bf16 v[136:139], v[112:115], v[160:163], v[136:139]
	v_mfma_f32_16x16x32_bf16 v[136:139], v[116:119], v[164:167], v[136:139]
	v_mfma_f32_16x16x32_bf16 v[124:127], v[104:107], v[196:199], v[124:127]
	v_mfma_f32_16x16x32_bf16 v[124:127], v[108:111], v[200:203], v[124:127]
	v_mfma_f32_16x16x32_bf16 v[120:123], v[112:115], v[196:199], v[120:123]
	v_mfma_f32_16x16x32_bf16 v[120:123], v[116:119], v[200:203], v[120:123]
	v_mfma_f32_16x16x32_bf16 v[92:95], v[104:107], v[210:213], v[92:95]
	v_mfma_f32_16x16x32_bf16 v[92:95], v[108:111], v[214:217], v[92:95]
	v_mfma_f32_16x16x32_bf16 v[88:91], v[112:115], v[210:213], v[88:91]
	v_mfma_f32_16x16x32_bf16 v[88:91], v[116:119], v[214:217], v[88:91]
	v_mfma_f32_16x16x32_bf16 v[80:83], v[104:107], v[218:221], v[80:83]
	v_mfma_f32_16x16x32_bf16 v[80:83], v[108:111], v[222:225], v[80:83]
	v_mfma_f32_16x16x32_bf16 v[76:79], v[112:115], v[218:221], v[76:79]
	v_mfma_f32_16x16x32_bf16 v[76:79], v[116:119], v[222:225], v[76:79]
	v_mfma_f32_16x16x32_bf16 v[132:135], v[144:147], v[160:163], v[132:135]
	v_mfma_f32_16x16x32_bf16 v[132:135], v[148:151], v[164:167], v[132:135]
	v_mfma_f32_16x16x32_bf16 v[128:131], v[152:155], v[160:163], v[128:131]
	v_mfma_f32_16x16x32_bf16 v[128:131], v[156:159], v[164:167], v[128:131]
	v_mfma_f32_16x16x32_bf16 v[100:103], v[144:147], v[196:199], v[100:103]
	v_mfma_f32_16x16x32_bf16 v[100:103], v[148:151], v[200:203], v[100:103]
	v_mfma_f32_16x16x32_bf16 v[96:99], v[152:155], v[196:199], v[96:99]
	v_mfma_f32_16x16x32_bf16 v[96:99], v[156:159], v[200:203], v[96:99]
	v_mfma_f32_16x16x32_bf16 v[84:87], v[144:147], v[210:213], v[84:87]
	v_mfma_f32_16x16x32_bf16 v[84:87], v[148:151], v[214:217], v[84:87]
	v_mfma_f32_16x16x32_bf16 v[72:75], v[152:155], v[210:213], v[72:75]
	v_mfma_f32_16x16x32_bf16 v[72:75], v[156:159], v[214:217], v[72:75]
	v_mfma_f32_16x16x32_bf16 v[68:71], v[144:147], v[218:221], v[68:71]
	v_mfma_f32_16x16x32_bf16 v[68:71], v[148:151], v[222:225], v[68:71]
	s_setprio 3
	s_barrier
	v_mfma_f32_16x16x32_bf16 v[64:67], v[152:155], v[218:221], v[64:67]
	v_mfma_f32_16x16x32_bf16 v[64:67], v[156:159], v[222:225], v[64:67]
	s_setprio 0
	s_add_i32 s61, s61, s30
	v_lshl_add_u64 v[190:191], s[2:3], 0, v[174:175]
	s_mov_b32 m0, s61
	ds_read_b128 v[160:163], v194 offset:16384
	ds_read_b128 v[164:167], v194 offset:17408
	ds_read_b128 v[196:199], v194 offset:18432
	ds_read_b128 v[200:203], v194 offset:19456
	ds_read_b128 v[210:213], v194 offset:20480
	ds_read_b128 v[214:217], v194 offset:21504
	ds_read_b128 v[218:221], v194 offset:22528
	ds_read_b128 v[222:225], v194 offset:23552
	global_load_lds_dwordx4 v[190:191], off
	s_add_i32 m0, s61, 0x2000
	v_lshl_add_u64 v[226:227], s[2:3], 0, v[184:185]
	s_add_u32 s2, s2, s27
	s_addc_u32 s3, s3, 0
	s_add_i32 s61, s62, s30
	global_load_lds_dwordx4 v[226:227], off
	v_lshl_add_u64 v[228:229], s[2:3], 0, v[174:175]
	s_mov_b32 m0, s61
	v_lshl_add_u64 v[230:231], s[2:3], 0, v[184:185]
	global_load_lds_dwordx4 v[228:229], off
	s_add_i32 m0, s61, 0x2000
	v_lshl_add_u64 v[232:233], s[24:25], 0, v[168:169]
	global_load_lds_dwordx4 v[230:231], off
	s_mov_b32 m0, s31
	v_lshl_add_u64 v[234:235], s[24:25], 0, v[170:171]
	global_load_lds_dwordx4 v[232:233], off
	s_mov_b32 m0, s34
	s_nop 0
	global_load_lds_dwordx4 v[234:235], off
	s_waitcnt vmcnt(40)
	s_waitcnt lgkmcnt(0)
	s_setprio 1
	s_barrier
	v_mfma_f32_16x16x32_bf16 v[60:63], v[104:107], v[160:163], v[60:63]
	v_mfma_f32_16x16x32_bf16 v[60:63], v[108:111], v[164:167], v[60:63]
	v_mfma_f32_16x16x32_bf16 v[56:59], v[112:115], v[160:163], v[56:59]
	v_mfma_f32_16x16x32_bf16 v[56:59], v[116:119], v[164:167], v[56:59]
	v_mfma_f32_16x16x32_bf16 v[44:47], v[104:107], v[196:199], v[44:47]
	v_mfma_f32_16x16x32_bf16 v[44:47], v[108:111], v[200:203], v[44:47]
	v_mfma_f32_16x16x32_bf16 v[40:43], v[112:115], v[196:199], v[40:43]
	v_mfma_f32_16x16x32_bf16 v[40:43], v[116:119], v[200:203], v[40:43]
	v_mfma_f32_16x16x32_bf16 v[36:39], v[104:107], v[210:213], v[36:39]
	v_mfma_f32_16x16x32_bf16 v[36:39], v[108:111], v[214:217], v[36:39]
	v_mfma_f32_16x16x32_bf16 v[28:31], v[112:115], v[210:213], v[28:31]
	v_mfma_f32_16x16x32_bf16 v[28:31], v[116:119], v[214:217], v[28:31]
	v_mfma_f32_16x16x32_bf16 v[20:23], v[104:107], v[218:221], v[20:23]
	v_mfma_f32_16x16x32_bf16 v[20:23], v[108:111], v[222:225], v[20:23]
	v_mfma_f32_16x16x32_bf16 v[12:15], v[112:115], v[218:221], v[12:15]
	v_mfma_f32_16x16x32_bf16 v[12:15], v[116:119], v[222:225], v[12:15]
	v_mfma_f32_16x16x32_bf16 v[52:55], v[144:147], v[160:163], v[52:55]
	v_mfma_f32_16x16x32_bf16 v[52:55], v[148:151], v[164:167], v[52:55]
	v_mfma_f32_16x16x32_bf16 v[48:51], v[152:155], v[160:163], v[48:51]
	v_mfma_f32_16x16x32_bf16 v[48:51], v[156:159], v[164:167], v[48:51]
	v_mfma_f32_16x16x32_bf16 v[32:35], v[144:147], v[196:199], v[32:35]
	v_mfma_f32_16x16x32_bf16 v[32:35], v[148:151], v[200:203], v[32:35]
	v_mfma_f32_16x16x32_bf16 v[24:27], v[152:155], v[196:199], v[24:27]
	v_mfma_f32_16x16x32_bf16 v[24:27], v[156:159], v[200:203], v[24:27]
	v_mfma_f32_16x16x32_bf16 v[16:19], v[144:147], v[210:213], v[16:19]
	v_mfma_f32_16x16x32_bf16 v[16:19], v[148:151], v[214:217], v[16:19]
	v_mfma_f32_16x16x32_bf16 v[8:11], v[152:155], v[210:213], v[8:11]
	v_mfma_f32_16x16x32_bf16 v[8:11], v[156:159], v[214:217], v[8:11]
	v_mfma_f32_16x16x32_bf16 v[4:7], v[144:147], v[218:221], v[4:7]
	v_mfma_f32_16x16x32_bf16 v[4:7], v[148:151], v[222:225], v[4:7]
	s_setprio 3
	s_barrier
	v_mfma_f32_16x16x32_bf16 v[0:3], v[152:155], v[218:221], v[0:3]
	v_mfma_f32_16x16x32_bf16 v[0:3], v[156:159], v[222:225], v[0:3]
	s_setprio 0
	s_add_i32 s61, 0, 0x18000
	s_add_i32 s62, 0, 0x1c000
	v_add_u32_e32 v116, s61, v192
	v_add_u32_e32 v156, s62, v192
	ds_read_b128 v[104:107], v116
	ds_read_b128 v[108:111], v116 offset:1024
	ds_read_b128 v[112:115], v116 offset:2048
	ds_read_b128 v[116:119], v116 offset:3072
	ds_read_b128 v[144:147], v156
	ds_read_b128 v[148:151], v156 offset:1024
	ds_read_b128 v[152:155], v156 offset:2048
	ds_read_b128 v[156:159], v156 offset:3072
	s_add_u32 s2, s24, s78
	s_addc_u32 s3, s25, 0
	s_mov_b32 m0, s35
	v_lshl_add_u64 v[236:237], s[2:3], 0, v[168:169]
	ds_read_b128 v[160:163], v194 offset:32768
	ds_read_b128 v[164:167], v194 offset:33792
	ds_read_b128 v[196:199], v194 offset:34816
	ds_read_b128 v[200:203], v194 offset:35840
	ds_read_b128 v[210:213], v194 offset:36864
	ds_read_b128 v[214:217], v194 offset:37888
	ds_read_b128 v[218:221], v194 offset:38912
	ds_read_b128 v[222:225], v194 offset:39936
	global_load_lds_dwordx4 v[236:237], off
	v_lshl_add_u64 v[236:237], s[2:3], 0, v[170:171]
	s_mov_b32 m0, s36
	s_nop 0
	global_load_lds_dwordx4 v[236:237], off
	s_waitcnt vmcnt(8)
	s_waitcnt lgkmcnt(0)
	s_setprio 1
	s_barrier
	v_mfma_f32_16x16x32_bf16 v[140:143], v[104:107], v[160:163], v[140:143]
	v_mfma_f32_16x16x32_bf16 v[140:143], v[108:111], v[164:167], v[140:143]
	v_mfma_f32_16x16x32_bf16 v[136:139], v[112:115], v[160:163], v[136:139]
	v_mfma_f32_16x16x32_bf16 v[136:139], v[116:119], v[164:167], v[136:139]
	v_mfma_f32_16x16x32_bf16 v[124:127], v[104:107], v[196:199], v[124:127]
	v_mfma_f32_16x16x32_bf16 v[124:127], v[108:111], v[200:203], v[124:127]
	v_mfma_f32_16x16x32_bf16 v[120:123], v[112:115], v[196:199], v[120:123]
	v_mfma_f32_16x16x32_bf16 v[120:123], v[116:119], v[200:203], v[120:123]
	v_mfma_f32_16x16x32_bf16 v[92:95], v[104:107], v[210:213], v[92:95]
	v_mfma_f32_16x16x32_bf16 v[92:95], v[108:111], v[214:217], v[92:95]
	v_mfma_f32_16x16x32_bf16 v[88:91], v[112:115], v[210:213], v[88:91]
	v_mfma_f32_16x16x32_bf16 v[88:91], v[116:119], v[214:217], v[88:91]
	v_mfma_f32_16x16x32_bf16 v[80:83], v[104:107], v[218:221], v[80:83]
	v_mfma_f32_16x16x32_bf16 v[80:83], v[108:111], v[222:225], v[80:83]
	v_mfma_f32_16x16x32_bf16 v[76:79], v[112:115], v[218:221], v[76:79]
	v_mfma_f32_16x16x32_bf16 v[76:79], v[116:119], v[222:225], v[76:79]
	v_mfma_f32_16x16x32_bf16 v[132:135], v[144:147], v[160:163], v[132:135]
	v_mfma_f32_16x16x32_bf16 v[132:135], v[148:151], v[164:167], v[132:135]
	v_mfma_f32_16x16x32_bf16 v[128:131], v[152:155], v[160:163], v[128:131]
	v_mfma_f32_16x16x32_bf16 v[128:131], v[156:159], v[164:167], v[128:131]
	v_mfma_f32_16x16x32_bf16 v[100:103], v[144:147], v[196:199], v[100:103]
	v_mfma_f32_16x16x32_bf16 v[100:103], v[148:151], v[200:203], v[100:103]
	v_mfma_f32_16x16x32_bf16 v[96:99], v[152:155], v[196:199], v[96:99]
	v_mfma_f32_16x16x32_bf16 v[96:99], v[156:159], v[200:203], v[96:99]
	v_mfma_f32_16x16x32_bf16 v[84:87], v[144:147], v[210:213], v[84:87]
	v_mfma_f32_16x16x32_bf16 v[84:87], v[148:151], v[214:217], v[84:87]
	v_mfma_f32_16x16x32_bf16 v[72:75], v[152:155], v[210:213], v[72:75]
	v_mfma_f32_16x16x32_bf16 v[72:75], v[156:159], v[214:217], v[72:75]
	v_mfma_f32_16x16x32_bf16 v[68:71], v[144:147], v[218:221], v[68:71]
	v_mfma_f32_16x16x32_bf16 v[68:71], v[148:151], v[222:225], v[68:71]
	s_setprio 3
	s_barrier
	v_mfma_f32_16x16x32_bf16 v[64:67], v[152:155], v[218:221], v[64:67]
	v_mfma_f32_16x16x32_bf16 v[64:67], v[156:159], v[222:225], v[64:67]
	s_setprio 0
	s_add_i32 s2, s61, s30
	v_lshl_add_u64 v[190:191], v[190:191], 0, s[82:83]
	s_mov_b32 m0, s2
	ds_read_b128 v[160:163], v194 offset:49152
	ds_read_b128 v[164:167], v194 offset:50176
	ds_read_b128 v[196:199], v194 offset:51200
	ds_read_b128 v[200:203], v194 offset:52224
	ds_read_b128 v[210:213], v194 offset:53248
	ds_read_b128 v[214:217], v194 offset:54272
	ds_read_b128 v[218:221], v194 offset:55296
	ds_read_b128 v[222:225], v194 offset:56320
	global_load_lds_dwordx4 v[190:191], off
	v_lshl_add_u64 v[190:191], v[226:227], 0, s[82:83]
	s_add_i32 m0, s2, 0x2000
	s_add_i32 s2, s62, s30
	global_load_lds_dwordx4 v[190:191], off
	v_lshl_add_u64 v[190:191], v[228:229], 0, s[82:83]
	s_mov_b32 m0, s2
	s_nop 0
	global_load_lds_dwordx4 v[190:191], off
	v_lshl_add_u64 v[190:191], v[230:231], 0, s[82:83]
	s_add_i32 m0, s2, 0x2000
	s_nop 0
	global_load_lds_dwordx4 v[190:191], off
	v_lshl_add_u64 v[190:191], v[232:233], 0, s[82:83]
	s_mov_b32 m0, s47
	s_nop 0
	global_load_lds_dwordx4 v[190:191], off
	v_lshl_add_u64 v[190:191], v[234:235], 0, s[82:83]
	s_mov_b32 m0, s50
	s_nop 0
	global_load_lds_dwordx4 v[190:191], off
	s_waitcnt vmcnt(8)
	s_waitcnt lgkmcnt(0)
	s_setprio 1
	s_barrier
	v_mfma_f32_16x16x32_bf16 v[60:63], v[104:107], v[160:163], v[60:63]
	v_mfma_f32_16x16x32_bf16 v[60:63], v[108:111], v[164:167], v[60:63]
	v_mfma_f32_16x16x32_bf16 v[56:59], v[112:115], v[160:163], v[56:59]
	v_mfma_f32_16x16x32_bf16 v[56:59], v[116:119], v[164:167], v[56:59]
	v_mfma_f32_16x16x32_bf16 v[44:47], v[104:107], v[196:199], v[44:47]
	v_mfma_f32_16x16x32_bf16 v[44:47], v[108:111], v[200:203], v[44:47]
	v_mfma_f32_16x16x32_bf16 v[40:43], v[112:115], v[196:199], v[40:43]
	v_mfma_f32_16x16x32_bf16 v[40:43], v[116:119], v[200:203], v[40:43]
	v_mfma_f32_16x16x32_bf16 v[36:39], v[104:107], v[210:213], v[36:39]
	v_mfma_f32_16x16x32_bf16 v[36:39], v[108:111], v[214:217], v[36:39]
	v_mfma_f32_16x16x32_bf16 v[28:31], v[112:115], v[210:213], v[28:31]
	v_mfma_f32_16x16x32_bf16 v[28:31], v[116:119], v[214:217], v[28:31]
	v_mfma_f32_16x16x32_bf16 v[20:23], v[104:107], v[218:221], v[20:23]
	v_mfma_f32_16x16x32_bf16 v[20:23], v[108:111], v[222:225], v[20:23]
	v_mfma_f32_16x16x32_bf16 v[12:15], v[112:115], v[218:221], v[12:15]
	v_mfma_f32_16x16x32_bf16 v[12:15], v[116:119], v[222:225], v[12:15]
	v_mfma_f32_16x16x32_bf16 v[52:55], v[144:147], v[160:163], v[52:55]
	v_mfma_f32_16x16x32_bf16 v[52:55], v[148:151], v[164:167], v[52:55]
	v_mfma_f32_16x16x32_bf16 v[48:51], v[152:155], v[160:163], v[48:51]
	v_mfma_f32_16x16x32_bf16 v[48:51], v[156:159], v[164:167], v[48:51]
	v_mfma_f32_16x16x32_bf16 v[32:35], v[144:147], v[196:199], v[32:35]
	v_mfma_f32_16x16x32_bf16 v[32:35], v[148:151], v[200:203], v[32:35]
	v_mfma_f32_16x16x32_bf16 v[24:27], v[152:155], v[196:199], v[24:27]
	v_mfma_f32_16x16x32_bf16 v[24:27], v[156:159], v[200:203], v[24:27]
	v_mfma_f32_16x16x32_bf16 v[16:19], v[144:147], v[210:213], v[16:19]
	v_mfma_f32_16x16x32_bf16 v[16:19], v[148:151], v[214:217], v[16:19]
	v_mfma_f32_16x16x32_bf16 v[8:11], v[152:155], v[210:213], v[8:11]
	v_mfma_f32_16x16x32_bf16 v[8:11], v[156:159], v[214:217], v[8:11]
	v_mfma_f32_16x16x32_bf16 v[4:7], v[144:147], v[218:221], v[4:7]
	v_mfma_f32_16x16x32_bf16 v[4:7], v[148:151], v[222:225], v[4:7]
	s_setprio 3
	s_barrier
	v_mfma_f32_16x16x32_bf16 v[0:3], v[152:155], v[218:221], v[0:3]
	v_mfma_f32_16x16x32_bf16 v[0:3], v[156:159], v[222:225], v[0:3]
	s_setprio 0
	s_add_u32 s57, s57, 0x100
	s_addc_u32 s59, s59, 0
	s_add_u32 s22, s22, 0x100
	s_addc_u32 s23, s23, 0
	s_cmp_ge_u32 s60, s46
	s_mov_b32 s24, s60
	s_cbranch_scc1 .Lexit_183
.LBB0_183:
	s_add_i32 s60, s24, 2
	s_add_u32 s2, s22, 0x80
	s_addc_u32 s3, s23, 0
	s_add_i32 s61, 0, 0x10000
	s_cmp_eq_u32 s51, s24
	s_cselect_b32 s25, s1, s3
	s_cselect_b32 s24, s0, s2
	s_cselect_b32 s3, s21, s59
	s_cselect_b32 s2, s20, s57
	s_add_i32 s62, 0, 0x14000
	v_add_u32_e32 v116, s61, v192
	v_add_u32_e32 v156, s62, v192
	ds_read_b128 v[104:107], v116
	ds_read_b128 v[108:111], v116 offset:1024
	ds_read_b128 v[112:115], v116 offset:2048
	ds_read_b128 v[116:119], v116 offset:3072
	ds_read_b128 v[144:147], v156
	ds_read_b128 v[148:151], v156 offset:1024
	ds_read_b128 v[152:155], v156 offset:2048
	ds_read_b128 v[156:159], v156 offset:3072
	v_lshl_add_u64 v[190:191], s[22:23], 0, v[188:189]
	s_add_i32 m0, s31, 0xc000
	ds_read_b128 v[160:163], v194
	ds_read_b128 v[164:167], v194 offset:1024
	ds_read_b128 v[196:199], v194 offset:2048
	ds_read_b128 v[200:203], v194 offset:3072
	ds_read_b128 v[210:213], v194 offset:4096
	ds_read_b128 v[214:217], v194 offset:5120
	ds_read_b128 v[218:221], v194 offset:6144
	ds_read_b128 v[222:225], v194 offset:7168
	global_load_lds_dwordx4 v[190:191], off
	v_lshl_add_u64 v[190:191], s[22:23], 0, v[186:187]
	s_add_i32 m0, s31, 0xe000
	s_nop 0
	global_load_lds_dwordx4 v[190:191], off
	s_waitcnt vmcnt(8)
	s_waitcnt lgkmcnt(0)
	s_setprio 1
	s_barrier
	v_mfma_f32_16x16x32_bf16 v[140:143], v[104:107], v[160:163], v[140:143]
	v_mfma_f32_16x16x32_bf16 v[140:143], v[108:111], v[164:167], v[140:143]
	v_mfma_f32_16x16x32_bf16 v[136:139], v[112:115], v[160:163], v[136:139]
	v_mfma_f32_16x16x32_bf16 v[136:139], v[116:119], v[164:167], v[136:139]
	v_mfma_f32_16x16x32_bf16 v[124:127], v[104:107], v[196:199], v[124:127]
	v_mfma_f32_16x16x32_bf16 v[124:127], v[108:111], v[200:203], v[124:127]
	v_mfma_f32_16x16x32_bf16 v[120:123], v[112:115], v[196:199], v[120:123]
	v_mfma_f32_16x16x32_bf16 v[120:123], v[116:119], v[200:203], v[120:123]
	v_mfma_f32_16x16x32_bf16 v[92:95], v[104:107], v[210:213], v[92:95]
	v_mfma_f32_16x16x32_bf16 v[92:95], v[108:111], v[214:217], v[92:95]
	v_mfma_f32_16x16x32_bf16 v[88:91], v[112:115], v[210:213], v[88:91]
	v_mfma_f32_16x16x32_bf16 v[88:91], v[116:119], v[214:217], v[88:91]
	v_mfma_f32_16x16x32_bf16 v[80:83], v[104:107], v[218:221], v[80:83]
	v_mfma_f32_16x16x32_bf16 v[80:83], v[108:111], v[222:225], v[80:83]
	v_mfma_f32_16x16x32_bf16 v[76:79], v[112:115], v[218:221], v[76:79]
	v_mfma_f32_16x16x32_bf16 v[76:79], v[116:119], v[222:225], v[76:79]
	v_mfma_f32_16x16x32_bf16 v[132:135], v[144:147], v[160:163], v[132:135]
	v_mfma_f32_16x16x32_bf16 v[132:135], v[148:151], v[164:167], v[132:135]
	v_mfma_f32_16x16x32_bf16 v[128:131], v[152:155], v[160:163], v[128:131]
	v_mfma_f32_16x16x32_bf16 v[128:131], v[156:159], v[164:167], v[128:131]
	v_mfma_f32_16x16x32_bf16 v[100:103], v[144:147], v[196:199], v[100:103]
	v_mfma_f32_16x16x32_bf16 v[100:103], v[148:151], v[200:203], v[100:103]
	v_mfma_f32_16x16x32_bf16 v[96:99], v[152:155], v[196:199], v[96:99]
	v_mfma_f32_16x16x32_bf16 v[96:99], v[156:159], v[200:203], v[96:99]
	v_mfma_f32_16x16x32_bf16 v[84:87], v[144:147], v[210:213], v[84:87]
	v_mfma_f32_16x16x32_bf16 v[84:87], v[148:151], v[214:217], v[84:87]
	v_mfma_f32_16x16x32_bf16 v[72:75], v[152:155], v[210:213], v[72:75]
	v_mfma_f32_16x16x32_bf16 v[72:75], v[156:159], v[214:217], v[72:75]
	v_mfma_f32_16x16x32_bf16 v[68:71], v[144:147], v[218:221], v[68:71]
	v_mfma_f32_16x16x32_bf16 v[68:71], v[148:151], v[222:225], v[68:71]
	s_setprio 3
	s_barrier
	v_mfma_f32_16x16x32_bf16 v[64:67], v[152:155], v[218:221], v[64:67]
	v_mfma_f32_16x16x32_bf16 v[64:67], v[156:159], v[222:225], v[64:67]
	s_setprio 0
	s_add_i32 s61, s61, s30
	v_lshl_add_u64 v[190:191], s[2:3], 0, v[174:175]
	s_mov_b32 m0, s61
	ds_read_b128 v[160:163], v194 offset:16384
	ds_read_b128 v[164:167], v194 offset:17408
	ds_read_b128 v[196:199], v194 offset:18432
	ds_read_b128 v[200:203], v194 offset:19456
	ds_read_b128 v[210:213], v194 offset:20480
	ds_read_b128 v[214:217], v194 offset:21504
	ds_read_b128 v[218:221], v194 offset:22528
	ds_read_b128 v[222:225], v194 offset:23552
	global_load_lds_dwordx4 v[190:191], off
	s_add_i32 m0, s61, 0x2000
	v_lshl_add_u64 v[226:227], s[2:3], 0, v[184:185]
	s_add_u32 s2, s2, s27
	s_addc_u32 s3, s3, 0
	s_add_i32 s61, s62, s30
	global_load_lds_dwordx4 v[226:227], off
	v_lshl_add_u64 v[228:229], s[2:3], 0, v[174:175]
	s_mov_b32 m0, s61
	v_lshl_add_u64 v[230:231], s[2:3], 0, v[184:185]
	global_load_lds_dwordx4 v[228:229], off
	s_add_i32 m0, s61, 0x2000
	v_lshl_add_u64 v[232:233], s[24:25], 0, v[168:169]
	global_load_lds_dwordx4 v[230:231], off
	s_mov_b32 m0, s31
	v_lshl_add_u64 v[234:235], s[24:25], 0, v[170:171]
	global_load_lds_dwordx4 v[232:233], off
	s_mov_b32 m0, s34
	s_nop 0
	global_load_lds_dwordx4 v[234:235], off
	s_waitcnt vmcnt(8)
	s_waitcnt lgkmcnt(0)
	s_setprio 1
	s_barrier
	v_mfma_f32_16x16x32_bf16 v[60:63], v[104:107], v[160:163], v[60:63]
	v_mfma_f32_16x16x32_bf16 v[60:63], v[108:111], v[164:167], v[60:63]
	v_mfma_f32_16x16x32_bf16 v[56:59], v[112:115], v[160:163], v[56:59]
	v_mfma_f32_16x16x32_bf16 v[56:59], v[116:119], v[164:167], v[56:59]
	v_mfma_f32_16x16x32_bf16 v[44:47], v[104:107], v[196:199], v[44:47]
	v_mfma_f32_16x16x32_bf16 v[44:47], v[108:111], v[200:203], v[44:47]
	v_mfma_f32_16x16x32_bf16 v[40:43], v[112:115], v[196:199], v[40:43]
	v_mfma_f32_16x16x32_bf16 v[40:43], v[116:119], v[200:203], v[40:43]
	v_mfma_f32_16x16x32_bf16 v[36:39], v[104:107], v[210:213], v[36:39]
	v_mfma_f32_16x16x32_bf16 v[36:39], v[108:111], v[214:217], v[36:39]
	v_mfma_f32_16x16x32_bf16 v[28:31], v[112:115], v[210:213], v[28:31]
	v_mfma_f32_16x16x32_bf16 v[28:31], v[116:119], v[214:217], v[28:31]
	v_mfma_f32_16x16x32_bf16 v[20:23], v[104:107], v[218:221], v[20:23]
	v_mfma_f32_16x16x32_bf16 v[20:23], v[108:111], v[222:225], v[20:23]
	v_mfma_f32_16x16x32_bf16 v[12:15], v[112:115], v[218:221], v[12:15]
	v_mfma_f32_16x16x32_bf16 v[12:15], v[116:119], v[222:225], v[12:15]
	v_mfma_f32_16x16x32_bf16 v[52:55], v[144:147], v[160:163], v[52:55]
	v_mfma_f32_16x16x32_bf16 v[52:55], v[148:151], v[164:167], v[52:55]
	v_mfma_f32_16x16x32_bf16 v[48:51], v[152:155], v[160:163], v[48:51]
	v_mfma_f32_16x16x32_bf16 v[48:51], v[156:159], v[164:167], v[48:51]
	v_mfma_f32_16x16x32_bf16 v[32:35], v[144:147], v[196:199], v[32:35]
	v_mfma_f32_16x16x32_bf16 v[32:35], v[148:151], v[200:203], v[32:35]
	v_mfma_f32_16x16x32_bf16 v[24:27], v[152:155], v[196:199], v[24:27]
	v_mfma_f32_16x16x32_bf16 v[24:27], v[156:159], v[200:203], v[24:27]
	v_mfma_f32_16x16x32_bf16 v[16:19], v[144:147], v[210:213], v[16:19]
	v_mfma_f32_16x16x32_bf16 v[16:19], v[148:151], v[214:217], v[16:19]
	v_mfma_f32_16x16x32_bf16 v[8:11], v[152:155], v[210:213], v[8:11]
	v_mfma_f32_16x16x32_bf16 v[8:11], v[156:159], v[214:217], v[8:11]
	v_mfma_f32_16x16x32_bf16 v[4:7], v[144:147], v[218:221], v[4:7]
	v_mfma_f32_16x16x32_bf16 v[4:7], v[148:151], v[222:225], v[4:7]
	s_setprio 3
	s_barrier
	v_mfma_f32_16x16x32_bf16 v[0:3], v[152:155], v[218:221], v[0:3]
	v_mfma_f32_16x16x32_bf16 v[0:3], v[156:159], v[222:225], v[0:3]
	s_setprio 0
	s_add_i32 s61, 0, 0x18000
	s_add_i32 s62, 0, 0x1c000
	v_add_u32_e32 v116, s61, v192
	v_add_u32_e32 v156, s62, v192
	ds_read_b128 v[104:107], v116
	ds_read_b128 v[108:111], v116 offset:1024
	ds_read_b128 v[112:115], v116 offset:2048
	ds_read_b128 v[116:119], v116 offset:3072
	ds_read_b128 v[144:147], v156
	ds_read_b128 v[148:151], v156 offset:1024
	ds_read_b128 v[152:155], v156 offset:2048
	ds_read_b128 v[156:159], v156 offset:3072
	s_add_u32 s2, s24, s78
	s_addc_u32 s3, s25, 0
	s_mov_b32 m0, s35
	v_lshl_add_u64 v[236:237], s[2:3], 0, v[168:169]
	ds_read_b128 v[160:163], v194 offset:32768
	ds_read_b128 v[164:167], v194 offset:33792
	ds_read_b128 v[196:199], v194 offset:34816
	ds_read_b128 v[200:203], v194 offset:35840
	ds_read_b128 v[210:213], v194 offset:36864
	ds_read_b128 v[214:217], v194 offset:37888
	ds_read_b128 v[218:221], v194 offset:38912
	ds_read_b128 v[222:225], v194 offset:39936
	global_load_lds_dwordx4 v[236:237], off
	v_lshl_add_u64 v[236:237], s[2:3], 0, v[170:171]
	s_mov_b32 m0, s36
	s_nop 0
	global_load_lds_dwordx4 v[236:237], off
	s_waitcnt vmcnt(8)
	s_waitcnt lgkmcnt(0)
	s_setprio 1
	s_barrier
	v_mfma_f32_16x16x32_bf16 v[140:143], v[104:107], v[160:163], v[140:143]
	v_mfma_f32_16x16x32_bf16 v[140:143], v[108:111], v[164:167], v[140:143]
	v_mfma_f32_16x16x32_bf16 v[136:139], v[112:115], v[160:163], v[136:139]
	v_mfma_f32_16x16x32_bf16 v[136:139], v[116:119], v[164:167], v[136:139]
	v_mfma_f32_16x16x32_bf16 v[124:127], v[104:107], v[196:199], v[124:127]
	v_mfma_f32_16x16x32_bf16 v[124:127], v[108:111], v[200:203], v[124:127]
	v_mfma_f32_16x16x32_bf16 v[120:123], v[112:115], v[196:199], v[120:123]
	v_mfma_f32_16x16x32_bf16 v[120:123], v[116:119], v[200:203], v[120:123]
	v_mfma_f32_16x16x32_bf16 v[92:95], v[104:107], v[210:213], v[92:95]
	v_mfma_f32_16x16x32_bf16 v[92:95], v[108:111], v[214:217], v[92:95]
	v_mfma_f32_16x16x32_bf16 v[88:91], v[112:115], v[210:213], v[88:91]
	v_mfma_f32_16x16x32_bf16 v[88:91], v[116:119], v[214:217], v[88:91]
	v_mfma_f32_16x16x32_bf16 v[80:83], v[104:107], v[218:221], v[80:83]
	v_mfma_f32_16x16x32_bf16 v[80:83], v[108:111], v[222:225], v[80:83]
	v_mfma_f32_16x16x32_bf16 v[76:79], v[112:115], v[218:221], v[76:79]
	v_mfma_f32_16x16x32_bf16 v[76:79], v[116:119], v[222:225], v[76:79]
	v_mfma_f32_16x16x32_bf16 v[132:135], v[144:147], v[160:163], v[132:135]
	v_mfma_f32_16x16x32_bf16 v[132:135], v[148:151], v[164:167], v[132:135]
	v_mfma_f32_16x16x32_bf16 v[128:131], v[152:155], v[160:163], v[128:131]
	v_mfma_f32_16x16x32_bf16 v[128:131], v[156:159], v[164:167], v[128:131]
	v_mfma_f32_16x16x32_bf16 v[100:103], v[144:147], v[196:199], v[100:103]
	v_mfma_f32_16x16x32_bf16 v[100:103], v[148:151], v[200:203], v[100:103]
	v_mfma_f32_16x16x32_bf16 v[96:99], v[152:155], v[196:199], v[96:99]
	v_mfma_f32_16x16x32_bf16 v[96:99], v[156:159], v[200:203], v[96:99]
	v_mfma_f32_16x16x32_bf16 v[84:87], v[144:147], v[210:213], v[84:87]
	v_mfma_f32_16x16x32_bf16 v[84:87], v[148:151], v[214:217], v[84:87]
	v_mfma_f32_16x16x32_bf16 v[72:75], v[152:155], v[210:213], v[72:75]
	v_mfma_f32_16x16x32_bf16 v[72:75], v[156:159], v[214:217], v[72:75]
	v_mfma_f32_16x16x32_bf16 v[68:71], v[144:147], v[218:221], v[68:71]
	v_mfma_f32_16x16x32_bf16 v[68:71], v[148:151], v[222:225], v[68:71]
	s_setprio 3
	s_barrier
	v_mfma_f32_16x16x32_bf16 v[64:67], v[152:155], v[218:221], v[64:67]
	v_mfma_f32_16x16x32_bf16 v[64:67], v[156:159], v[222:225], v[64:67]
	s_setprio 0
	s_add_i32 s2, s61, s30
	v_lshl_add_u64 v[190:191], v[190:191], 0, s[82:83]
	s_mov_b32 m0, s2
	ds_read_b128 v[160:163], v194 offset:49152
	ds_read_b128 v[164:167], v194 offset:50176
	ds_read_b128 v[196:199], v194 offset:51200
	ds_read_b128 v[200:203], v194 offset:52224
	ds_read_b128 v[210:213], v194 offset:53248
	ds_read_b128 v[214:217], v194 offset:54272
	ds_read_b128 v[218:221], v194 offset:55296
	ds_read_b128 v[222:225], v194 offset:56320
	global_load_lds_dwordx4 v[190:191], off
	v_lshl_add_u64 v[190:191], v[226:227], 0, s[82:83]
	s_add_i32 m0, s2, 0x2000
	s_add_i32 s2, s62, s30
	global_load_lds_dwordx4 v[190:191], off
	v_lshl_add_u64 v[190:191], v[228:229], 0, s[82:83]
	s_mov_b32 m0, s2
	s_nop 0
	global_load_lds_dwordx4 v[190:191], off
	v_lshl_add_u64 v[190:191], v[230:231], 0, s[82:83]
	s_add_i32 m0, s2, 0x2000
	s_nop 0
	global_load_lds_dwordx4 v[190:191], off
	v_lshl_add_u64 v[190:191], v[232:233], 0, s[82:83]
	s_mov_b32 m0, s47
	s_nop 0
	global_load_lds_dwordx4 v[190:191], off
	v_lshl_add_u64 v[190:191], v[234:235], 0, s[82:83]
	s_mov_b32 m0, s50
	s_nop 0
	global_load_lds_dwordx4 v[190:191], off
	s_waitcnt vmcnt(8)
	s_waitcnt lgkmcnt(0)
	s_setprio 1
	s_barrier
	v_mfma_f32_16x16x32_bf16 v[60:63], v[104:107], v[160:163], v[60:63]
	v_mfma_f32_16x16x32_bf16 v[60:63], v[108:111], v[164:167], v[60:63]
	v_mfma_f32_16x16x32_bf16 v[56:59], v[112:115], v[160:163], v[56:59]
	v_mfma_f32_16x16x32_bf16 v[56:59], v[116:119], v[164:167], v[56:59]
	v_mfma_f32_16x16x32_bf16 v[44:47], v[104:107], v[196:199], v[44:47]
	v_mfma_f32_16x16x32_bf16 v[44:47], v[108:111], v[200:203], v[44:47]
	v_mfma_f32_16x16x32_bf16 v[40:43], v[112:115], v[196:199], v[40:43]
	v_mfma_f32_16x16x32_bf16 v[40:43], v[116:119], v[200:203], v[40:43]
	v_mfma_f32_16x16x32_bf16 v[36:39], v[104:107], v[210:213], v[36:39]
	v_mfma_f32_16x16x32_bf16 v[36:39], v[108:111], v[214:217], v[36:39]
	v_mfma_f32_16x16x32_bf16 v[28:31], v[112:115], v[210:213], v[28:31]
	v_mfma_f32_16x16x32_bf16 v[28:31], v[116:119], v[214:217], v[28:31]
	v_mfma_f32_16x16x32_bf16 v[20:23], v[104:107], v[218:221], v[20:23]
	v_mfma_f32_16x16x32_bf16 v[20:23], v[108:111], v[222:225], v[20:23]
	v_mfma_f32_16x16x32_bf16 v[12:15], v[112:115], v[218:221], v[12:15]
	v_mfma_f32_16x16x32_bf16 v[12:15], v[116:119], v[222:225], v[12:15]
	v_mfma_f32_16x16x32_bf16 v[52:55], v[144:147], v[160:163], v[52:55]
	v_mfma_f32_16x16x32_bf16 v[52:55], v[148:151], v[164:167], v[52:55]
	v_mfma_f32_16x16x32_bf16 v[48:51], v[152:155], v[160:163], v[48:51]
	v_mfma_f32_16x16x32_bf16 v[48:51], v[156:159], v[164:167], v[48:51]
	v_mfma_f32_16x16x32_bf16 v[32:35], v[144:147], v[196:199], v[32:35]
	v_mfma_f32_16x16x32_bf16 v[32:35], v[148:151], v[200:203], v[32:35]
	v_mfma_f32_16x16x32_bf16 v[24:27], v[152:155], v[196:199], v[24:27]
	v_mfma_f32_16x16x32_bf16 v[24:27], v[156:159], v[200:203], v[24:27]
	v_mfma_f32_16x16x32_bf16 v[16:19], v[144:147], v[210:213], v[16:19]
	v_mfma_f32_16x16x32_bf16 v[16:19], v[148:151], v[214:217], v[16:19]
	v_mfma_f32_16x16x32_bf16 v[8:11], v[152:155], v[210:213], v[8:11]
	v_mfma_f32_16x16x32_bf16 v[8:11], v[156:159], v[214:217], v[8:11]
	v_mfma_f32_16x16x32_bf16 v[4:7], v[144:147], v[218:221], v[4:7]
	v_mfma_f32_16x16x32_bf16 v[4:7], v[148:151], v[222:225], v[4:7]
	s_setprio 3
	s_barrier
	v_mfma_f32_16x16x32_bf16 v[0:3], v[152:155], v[218:221], v[0:3]
	v_mfma_f32_16x16x32_bf16 v[0:3], v[156:159], v[222:225], v[0:3]
	s_setprio 0
	s_add_u32 s57, s57, 0x100
	s_addc_u32 s59, s59, 0
	s_add_u32 s22, s22, 0x100
	s_addc_u32 s23, s23, 0
	s_cmp_ge_u32 s60, s46
	s_mov_b32 s24, s60
	s_cbranch_scc0 .LBB0_183

.LBB0_241:
	s_ashr_i32 s35, s34, 31
	s_lshl_b64 s[12:13], s[34:35], 19
	s_add_u32 s36, s40, s12
	s_addc_u32 s37, s41, s13
	s_and_b64 s[12:13], s[4:5], exec
	s_cselect_b32 s7, s37, s11
	s_cselect_b32 s35, s36, s10
	s_ashr_i32 s31, s30, 31
	s_lshl_b64 s[12:13], s[30:31], 19
	s_add_u32 s50, s42, s12
	s_addc_u32 s51, s43, s13
	s_and_b64 s[12:13], s[4:5], exec
	s_cselect_b32 s31, s51, s9
	s_cselect_b32 s89, s50, s8
	s_add_u32 vcc_lo, s8, 0x100
	s_addc_u32 vcc_hi, s9, 0
	s_add_u32 s8, s10, 0x40080
	v_mov_b32_e32 v0, 0
	s_addc_u32 s9, s11, 0
	s_mov_b32 s12, -2
	v_mov_b32_e32 v1, v0
	v_mov_b32_e32 v2, v0
	v_mov_b32_e32 v3, v0
	v_mov_b32_e32 v4, v0
	v_mov_b32_e32 v5, v0
	v_mov_b32_e32 v6, v0
	v_mov_b32_e32 v7, v0
	v_mov_b32_e32 v16, v0
	v_mov_b32_e32 v17, v0
	v_mov_b32_e32 v18, v0
	v_mov_b32_e32 v19, v0
	v_mov_b32_e32 v20, v0
	v_mov_b32_e32 v21, v0
	v_mov_b32_e32 v22, v0
	v_mov_b32_e32 v23, v0
	v_mov_b32_e32 v32, v0
	v_mov_b32_e32 v33, v0
	v_mov_b32_e32 v34, v0
	v_mov_b32_e32 v35, v0
	v_mov_b32_e32 v36, v0
	v_mov_b32_e32 v37, v0
	v_mov_b32_e32 v38, v0
	v_mov_b32_e32 v39, v0
	v_mov_b32_e32 v48, v0
	v_mov_b32_e32 v49, v0
	v_mov_b32_e32 v50, v0
	v_mov_b32_e32 v51, v0
	v_mov_b32_e32 v52, v0
	v_mov_b32_e32 v53, v0
	v_mov_b32_e32 v54, v0
	v_mov_b32_e32 v55, v0
	v_mov_b32_e32 v8, v0
	v_mov_b32_e32 v9, v0
	v_mov_b32_e32 v10, v0
	v_mov_b32_e32 v11, v0
	v_mov_b32_e32 v12, v0
	v_mov_b32_e32 v13, v0
	v_mov_b32_e32 v14, v0
	v_mov_b32_e32 v15, v0
	v_mov_b32_e32 v24, v0
	v_mov_b32_e32 v25, v0
	v_mov_b32_e32 v26, v0
	v_mov_b32_e32 v27, v0
	v_mov_b32_e32 v28, v0
	v_mov_b32_e32 v29, v0
	v_mov_b32_e32 v30, v0
	v_mov_b32_e32 v31, v0
	v_mov_b32_e32 v40, v0
	v_mov_b32_e32 v41, v0
	v_mov_b32_e32 v42, v0
	v_mov_b32_e32 v43, v0
	v_mov_b32_e32 v44, v0
	v_mov_b32_e32 v45, v0
	v_mov_b32_e32 v46, v0
	v_mov_b32_e32 v47, v0
	v_mov_b32_e32 v56, v0
	v_mov_b32_e32 v57, v0
	v_mov_b32_e32 v58, v0
	v_mov_b32_e32 v59, v0
	v_mov_b32_e32 v60, v0
	v_mov_b32_e32 v61, v0
	v_mov_b32_e32 v62, v0
	v_mov_b32_e32 v63, v0
	v_mov_b32_e32 v64, v0
	v_mov_b32_e32 v65, v0
	v_mov_b32_e32 v66, v0
	v_mov_b32_e32 v67, v0
	v_mov_b32_e32 v68, v0
	v_mov_b32_e32 v69, v0
	v_mov_b32_e32 v70, v0
	v_mov_b32_e32 v71, v0
	v_mov_b32_e32 v80, v0
	v_mov_b32_e32 v81, v0
	v_mov_b32_e32 v82, v0
	v_mov_b32_e32 v83, v0
	v_mov_b32_e32 v84, v0
	v_mov_b32_e32 v85, v0
	v_mov_b32_e32 v86, v0
	v_mov_b32_e32 v87, v0
	v_mov_b32_e32 v96, v0
	v_mov_b32_e32 v97, v0
	v_mov_b32_e32 v98, v0
	v_mov_b32_e32 v99, v0
	v_mov_b32_e32 v100, v0
	v_mov_b32_e32 v101, v0
	v_mov_b32_e32 v102, v0
	v_mov_b32_e32 v103, v0
	v_mov_b32_e32 v112, v0
	v_mov_b32_e32 v113, v0
	v_mov_b32_e32 v114, v0
	v_mov_b32_e32 v115, v0
	v_mov_b32_e32 v116, v0
	v_mov_b32_e32 v117, v0
	v_mov_b32_e32 v118, v0
	v_mov_b32_e32 v119, v0
	v_mov_b32_e32 v72, v0
	v_mov_b32_e32 v73, v0
	v_mov_b32_e32 v74, v0
	v_mov_b32_e32 v75, v0
	v_mov_b32_e32 v76, v0
	v_mov_b32_e32 v77, v0
	v_mov_b32_e32 v78, v0
	v_mov_b32_e32 v79, v0
	v_mov_b32_e32 v88, v0
	v_mov_b32_e32 v89, v0
	v_mov_b32_e32 v90, v0
	v_mov_b32_e32 v91, v0
	v_mov_b32_e32 v92, v0
	v_mov_b32_e32 v93, v0
	v_mov_b32_e32 v94, v0
	v_mov_b32_e32 v95, v0
	v_mov_b32_e32 v104, v0
	v_mov_b32_e32 v105, v0
	v_mov_b32_e32 v106, v0
	v_mov_b32_e32 v107, v0
	v_mov_b32_e32 v108, v0
	v_mov_b32_e32 v109, v0
	v_mov_b32_e32 v110, v0
	v_mov_b32_e32 v111, v0
	v_mov_b32_e32 v120, v0
	v_mov_b32_e32 v121, v0
	v_mov_b32_e32 v122, v0
	v_mov_b32_e32 v123, v0
	v_mov_b32_e32 v124, v0
	v_mov_b32_e32 v125, v0
	v_mov_b32_e32 v126, v0
	v_mov_b32_e32 v127, v0
	v_readlane_b32 s2, v246, 42
	s_cmp_eq_u32 s2, 0
	s_cbranch_scc1 .LBB0_242
	s_add_u32 s2, s8, 0xfffc0080
	s_addc_u32 s3, s9, -1
	s_add_i32 s13, 0, 0x10000
	s_cmp_eq_u32 s12, 12
	s_cselect_b32 s53, s7, s3
	s_cselect_b32 s52, s35, s2
	v_add_u32_e32 v156, s13, v164
	s_cselect_b32 s11, s31, vcc_hi
	s_cselect_b32 s10, s89, vcc_lo
	s_add_i32 s77, 0, 0x14000
	ds_read_b128 v[144:147], v156
	ds_read_b128 v[148:151], v156 offset:1024
	ds_read_b128 v[152:155], v156 offset:2048
	ds_read_b128 v[166:169], v156 offset:3072
	v_add_u32_e32 v156, s77, v164
	ds_read_b128 v[184:187], v156
	ds_read_b128 v[188:191], v156 offset:1024
	ds_read_b128 v[192:195], v156 offset:2048
	ds_read_b128 v[196:199], v156 offset:3072
	v_lshl_add_u64 v[156:157], s[8:9], 0, v[142:143]
	s_add_i32 m0, s19, 0xc000
	ds_read_b128 v[200:203], v165
	ds_read_b128 v[210:213], v165 offset:1024
	ds_read_b128 v[214:217], v165 offset:2048
	ds_read_b128 v[218:221], v165 offset:3072
	ds_read_b128 v[222:225], v165 offset:4096
	ds_read_b128 v[226:229], v165 offset:5120
	ds_read_b128 v[230:233], v165 offset:6144
	ds_read_b128 v[234:237], v165 offset:7168
	global_load_lds_dwordx4 v[156:157], off
	v_lshl_add_u64 v[156:157], s[8:9], 0, v[140:141]
	s_add_i32 m0, s19, 0xe000
	s_nop 0
	global_load_lds_dwordx4 v[156:157], off
	s_waitcnt vmcnt(24)
	s_waitcnt lgkmcnt(0)
	s_setprio 1
	s_barrier
	v_mfma_f32_16x16x32_bf16 v[124:127], v[144:147], v[200:203], v[124:127]
	v_mfma_f32_16x16x32_bf16 v[124:127], v[148:151], v[210:213], v[124:127]
	v_mfma_f32_16x16x32_bf16 v[120:123], v[152:155], v[200:203], v[120:123]
	v_mfma_f32_16x16x32_bf16 v[120:123], v[166:169], v[210:213], v[120:123]
	v_mfma_f32_16x16x32_bf16 v[108:111], v[144:147], v[214:217], v[108:111]
	v_mfma_f32_16x16x32_bf16 v[108:111], v[148:151], v[218:221], v[108:111]
	v_mfma_f32_16x16x32_bf16 v[104:107], v[152:155], v[214:217], v[104:107]
	v_mfma_f32_16x16x32_bf16 v[104:107], v[166:169], v[218:221], v[104:107]
	v_mfma_f32_16x16x32_bf16 v[92:95], v[144:147], v[222:225], v[92:95]
	v_mfma_f32_16x16x32_bf16 v[92:95], v[148:151], v[226:229], v[92:95]
	v_mfma_f32_16x16x32_bf16 v[88:91], v[152:155], v[222:225], v[88:91]
	v_mfma_f32_16x16x32_bf16 v[88:91], v[166:169], v[226:229], v[88:91]
	v_mfma_f32_16x16x32_bf16 v[76:79], v[144:147], v[230:233], v[76:79]
	v_mfma_f32_16x16x32_bf16 v[76:79], v[148:151], v[234:237], v[76:79]
	v_mfma_f32_16x16x32_bf16 v[72:75], v[152:155], v[230:233], v[72:75]
	v_mfma_f32_16x16x32_bf16 v[72:75], v[166:169], v[234:237], v[72:75]
	v_mfma_f32_16x16x32_bf16 v[116:119], v[184:187], v[200:203], v[116:119]
	v_mfma_f32_16x16x32_bf16 v[116:119], v[188:191], v[210:213], v[116:119]
	v_mfma_f32_16x16x32_bf16 v[112:115], v[192:195], v[200:203], v[112:115]
	v_mfma_f32_16x16x32_bf16 v[112:115], v[196:199], v[210:213], v[112:115]
	v_mfma_f32_16x16x32_bf16 v[100:103], v[184:187], v[214:217], v[100:103]
	v_mfma_f32_16x16x32_bf16 v[100:103], v[188:191], v[218:221], v[100:103]
	v_mfma_f32_16x16x32_bf16 v[96:99], v[192:195], v[214:217], v[96:99]
	v_mfma_f32_16x16x32_bf16 v[96:99], v[196:199], v[218:221], v[96:99]
	v_mfma_f32_16x16x32_bf16 v[84:87], v[184:187], v[222:225], v[84:87]
	v_mfma_f32_16x16x32_bf16 v[84:87], v[188:191], v[226:229], v[84:87]
	v_mfma_f32_16x16x32_bf16 v[80:83], v[192:195], v[222:225], v[80:83]
	v_mfma_f32_16x16x32_bf16 v[80:83], v[196:199], v[226:229], v[80:83]
	v_mfma_f32_16x16x32_bf16 v[68:71], v[184:187], v[230:233], v[68:71]
	v_mfma_f32_16x16x32_bf16 v[68:71], v[188:191], v[234:237], v[68:71]
	s_setprio 3
	s_barrier
	v_mfma_f32_16x16x32_bf16 v[64:67], v[192:195], v[230:233], v[64:67]
	v_mfma_f32_16x16x32_bf16 v[64:67], v[196:199], v[234:237], v[64:67]
	s_setprio 0
	s_add_i32 s2, s13, s56
	v_lshl_add_u64 v[156:157], s[10:11], 0, v[174:175]
	s_mov_b32 m0, s2
	ds_read_b128 v[200:203], v165 offset:16384
	ds_read_b128 v[210:213], v165 offset:17408
	ds_read_b128 v[214:217], v165 offset:18432
	ds_read_b128 v[218:221], v165 offset:19456
	ds_read_b128 v[222:225], v165 offset:20480
	ds_read_b128 v[226:229], v165 offset:21504
	ds_read_b128 v[230:233], v165 offset:22528
	ds_read_b128 v[234:237], v165 offset:23552
	global_load_lds_dwordx4 v[156:157], off
	s_add_i32 m0, s2, 0x2000
	s_add_u32 s2, s10, 0x40000
	v_lshl_add_u64 v[170:171], s[10:11], 0, v[132:133]
	s_addc_u32 s3, s11, 0
	s_add_i32 s13, s77, s56
	global_load_lds_dwordx4 v[170:171], off
	v_lshl_add_u64 v[238:239], s[2:3], 0, v[174:175]
	s_mov_b32 m0, s13
	v_lshl_add_u64 v[240:241], s[52:53], 0, v[130:131]
	global_load_lds_dwordx4 v[238:239], off
	v_lshl_add_u64 v[238:239], s[2:3], 0, v[132:133]
	s_add_i32 m0, s13, 0x2000
	s_nop 0
	global_load_lds_dwordx4 v[238:239], off
	v_lshl_add_u64 v[238:239], s[52:53], 0, v[128:129]
	s_mov_b32 m0, s19
	s_nop 0
	global_load_lds_dwordx4 v[238:239], off
	s_mov_b32 m0, s57
	s_nop 0
	global_load_lds_dwordx4 v[240:241], off
	s_waitcnt vmcnt(24)
	s_waitcnt lgkmcnt(0)
	s_setprio 1
	s_barrier
	v_mfma_f32_16x16x32_bf16 v[60:63], v[144:147], v[200:203], v[60:63]
	v_mfma_f32_16x16x32_bf16 v[60:63], v[148:151], v[210:213], v[60:63]
	v_mfma_f32_16x16x32_bf16 v[56:59], v[152:155], v[200:203], v[56:59]
	v_mfma_f32_16x16x32_bf16 v[56:59], v[166:169], v[210:213], v[56:59]
	v_mfma_f32_16x16x32_bf16 v[44:47], v[144:147], v[214:217], v[44:47]
	v_mfma_f32_16x16x32_bf16 v[44:47], v[148:151], v[218:221], v[44:47]
	v_mfma_f32_16x16x32_bf16 v[40:43], v[152:155], v[214:217], v[40:43]
	v_mfma_f32_16x16x32_bf16 v[40:43], v[166:169], v[218:221], v[40:43]
	v_mfma_f32_16x16x32_bf16 v[28:31], v[144:147], v[222:225], v[28:31]
	v_mfma_f32_16x16x32_bf16 v[28:31], v[148:151], v[226:229], v[28:31]
	v_mfma_f32_16x16x32_bf16 v[24:27], v[152:155], v[222:225], v[24:27]
	v_mfma_f32_16x16x32_bf16 v[24:27], v[166:169], v[226:229], v[24:27]
	v_mfma_f32_16x16x32_bf16 v[12:15], v[144:147], v[230:233], v[12:15]
	v_mfma_f32_16x16x32_bf16 v[12:15], v[148:151], v[234:237], v[12:15]
	v_mfma_f32_16x16x32_bf16 v[8:11], v[152:155], v[230:233], v[8:11]
	v_mfma_f32_16x16x32_bf16 v[8:11], v[166:169], v[234:237], v[8:11]
	v_mfma_f32_16x16x32_bf16 v[52:55], v[184:187], v[200:203], v[52:55]
	v_mfma_f32_16x16x32_bf16 v[52:55], v[188:191], v[210:213], v[52:55]
	v_mfma_f32_16x16x32_bf16 v[48:51], v[192:195], v[200:203], v[48:51]
	v_mfma_f32_16x16x32_bf16 v[48:51], v[196:199], v[210:213], v[48:51]
	v_mfma_f32_16x16x32_bf16 v[36:39], v[184:187], v[214:217], v[36:39]
	v_mfma_f32_16x16x32_bf16 v[36:39], v[188:191], v[218:221], v[36:39]
	v_mfma_f32_16x16x32_bf16 v[32:35], v[192:195], v[214:217], v[32:35]
	v_mfma_f32_16x16x32_bf16 v[32:35], v[196:199], v[218:221], v[32:35]
	v_mfma_f32_16x16x32_bf16 v[20:23], v[184:187], v[222:225], v[20:23]
	v_mfma_f32_16x16x32_bf16 v[20:23], v[188:191], v[226:229], v[20:23]
	v_mfma_f32_16x16x32_bf16 v[16:19], v[192:195], v[222:225], v[16:19]
	v_mfma_f32_16x16x32_bf16 v[16:19], v[196:199], v[226:229], v[16:19]
	v_mfma_f32_16x16x32_bf16 v[4:7], v[184:187], v[230:233], v[4:7]
	v_mfma_f32_16x16x32_bf16 v[4:7], v[188:191], v[234:237], v[4:7]
	s_setprio 3
	s_barrier
	v_mfma_f32_16x16x32_bf16 v[0:3], v[192:195], v[230:233], v[0:3]
	v_mfma_f32_16x16x32_bf16 v[0:3], v[196:199], v[234:237], v[0:3]
	s_setprio 0
	s_add_i32 s13, 0, 0x18000
	s_add_i32 s77, 0, 0x1c000
	v_add_u32_e32 v166, s13, v164
	v_add_u32_e32 v183, s77, v164
	ds_read_b128 v[144:147], v166
	ds_read_b128 v[148:151], v166 offset:1024
	ds_read_b128 v[152:155], v166 offset:2048
	ds_read_b128 v[166:169], v166 offset:3072
	ds_read_b128 v[184:187], v183
	ds_read_b128 v[188:191], v183 offset:1024
	ds_read_b128 v[192:195], v183 offset:2048
	ds_read_b128 v[196:199], v183 offset:3072
	s_add_u32 s2, s52, 0x40000
	s_addc_u32 s3, s53, 0
	s_mov_b32 m0, s60
	v_lshl_add_u64 v[242:243], s[2:3], 0, v[128:129]
	ds_read_b128 v[200:203], v165 offset:32768
	ds_read_b128 v[210:213], v165 offset:33792
	ds_read_b128 v[214:217], v165 offset:34816
	ds_read_b128 v[218:221], v165 offset:35840
	ds_read_b128 v[222:225], v165 offset:36864
	ds_read_b128 v[226:229], v165 offset:37888
	ds_read_b128 v[230:233], v165 offset:38912
	ds_read_b128 v[234:237], v165 offset:39936
	global_load_lds_dwordx4 v[242:243], off
	v_lshl_add_u64 v[242:243], s[2:3], 0, v[130:131]
	s_mov_b32 m0, s61
	s_nop 0
	global_load_lds_dwordx4 v[242:243], off
	s_waitcnt vmcnt(8)
	s_waitcnt lgkmcnt(0)
	s_setprio 1
	s_barrier
	v_mfma_f32_16x16x32_bf16 v[124:127], v[144:147], v[200:203], v[124:127]
	v_mfma_f32_16x16x32_bf16 v[124:127], v[148:151], v[210:213], v[124:127]
	v_mfma_f32_16x16x32_bf16 v[120:123], v[152:155], v[200:203], v[120:123]
	v_mfma_f32_16x16x32_bf16 v[120:123], v[166:169], v[210:213], v[120:123]
	v_mfma_f32_16x16x32_bf16 v[108:111], v[144:147], v[214:217], v[108:111]
	v_mfma_f32_16x16x32_bf16 v[108:111], v[148:151], v[218:221], v[108:111]
	v_mfma_f32_16x16x32_bf16 v[104:107], v[152:155], v[214:217], v[104:107]
	v_mfma_f32_16x16x32_bf16 v[104:107], v[166:169], v[218:221], v[104:107]
	v_mfma_f32_16x16x32_bf16 v[92:95], v[144:147], v[222:225], v[92:95]
	v_mfma_f32_16x16x32_bf16 v[92:95], v[148:151], v[226:229], v[92:95]
	v_mfma_f32_16x16x32_bf16 v[88:91], v[152:155], v[222:225], v[88:91]
	v_mfma_f32_16x16x32_bf16 v[88:91], v[166:169], v[226:229], v[88:91]
	v_mfma_f32_16x16x32_bf16 v[76:79], v[144:147], v[230:233], v[76:79]
	v_mfma_f32_16x16x32_bf16 v[76:79], v[148:151], v[234:237], v[76:79]
	v_mfma_f32_16x16x32_bf16 v[72:75], v[152:155], v[230:233], v[72:75]
	v_mfma_f32_16x16x32_bf16 v[72:75], v[166:169], v[234:237], v[72:75]
	v_mfma_f32_16x16x32_bf16 v[116:119], v[184:187], v[200:203], v[116:119]
	v_mfma_f32_16x16x32_bf16 v[116:119], v[188:191], v[210:213], v[116:119]
	v_mfma_f32_16x16x32_bf16 v[112:115], v[192:195], v[200:203], v[112:115]
	v_mfma_f32_16x16x32_bf16 v[112:115], v[196:199], v[210:213], v[112:115]
	v_mfma_f32_16x16x32_bf16 v[100:103], v[184:187], v[214:217], v[100:103]
	v_mfma_f32_16x16x32_bf16 v[100:103], v[188:191], v[218:221], v[100:103]
	v_mfma_f32_16x16x32_bf16 v[96:99], v[192:195], v[214:217], v[96:99]
	v_mfma_f32_16x16x32_bf16 v[96:99], v[196:199], v[218:221], v[96:99]
	v_mfma_f32_16x16x32_bf16 v[84:87], v[184:187], v[222:225], v[84:87]
	v_mfma_f32_16x16x32_bf16 v[84:87], v[188:191], v[226:229], v[84:87]
	v_mfma_f32_16x16x32_bf16 v[80:83], v[192:195], v[222:225], v[80:83]
	v_mfma_f32_16x16x32_bf16 v[80:83], v[196:199], v[226:229], v[80:83]
	v_mfma_f32_16x16x32_bf16 v[68:71], v[184:187], v[230:233], v[68:71]
	v_mfma_f32_16x16x32_bf16 v[68:71], v[188:191], v[234:237], v[68:71]
	s_setprio 3
	s_barrier
	v_mfma_f32_16x16x32_bf16 v[64:67], v[192:195], v[230:233], v[64:67]
	v_mfma_f32_16x16x32_bf16 v[64:67], v[196:199], v[234:237], v[64:67]
	s_setprio 0
	s_add_i32 s2, s13, s56
	v_lshl_add_u64 v[156:157], v[156:157], 0, s[82:83]
	s_mov_b32 m0, s2
	ds_read_b128 v[200:203], v165 offset:49152
	ds_read_b128 v[210:213], v165 offset:50176
	ds_read_b128 v[214:217], v165 offset:51200
	ds_read_b128 v[218:221], v165 offset:52224
	ds_read_b128 v[222:225], v165 offset:53248
	ds_read_b128 v[226:229], v165 offset:54272
	ds_read_b128 v[230:233], v165 offset:55296
	ds_read_b128 v[234:237], v165 offset:56320
	global_load_lds_dwordx4 v[156:157], off
	s_add_i32 m0, s2, 0x2000
	s_add_u32 s2, s10, 0x40080
	v_lshl_add_u64 v[156:157], v[170:171], 0, s[82:83]
	s_addc_u32 s3, s11, 0
	s_add_i32 s10, s77, s56
	global_load_lds_dwordx4 v[156:157], off
	v_lshl_add_u64 v[156:157], s[2:3], 0, v[174:175]
	s_mov_b32 m0, s10
	s_nop 0
	global_load_lds_dwordx4 v[156:157], off
	v_lshl_add_u64 v[156:157], s[2:3], 0, v[132:133]
	s_add_i32 m0, s10, 0x2000
	s_nop 0
	global_load_lds_dwordx4 v[156:157], off
	v_lshl_add_u64 v[156:157], v[238:239], 0, s[82:83]
	s_mov_b32 m0, s39
	s_nop 0
	global_load_lds_dwordx4 v[156:157], off
	v_lshl_add_u64 v[156:157], v[240:241], 0, s[82:83]
	s_mov_b32 m0, s46
	s_nop 0
	global_load_lds_dwordx4 v[156:157], off
	s_waitcnt vmcnt(8)
	s_waitcnt lgkmcnt(0)
	s_setprio 1
	s_barrier
	v_mfma_f32_16x16x32_bf16 v[60:63], v[144:147], v[200:203], v[60:63]
	v_mfma_f32_16x16x32_bf16 v[60:63], v[148:151], v[210:213], v[60:63]
	v_mfma_f32_16x16x32_bf16 v[56:59], v[152:155], v[200:203], v[56:59]
	v_mfma_f32_16x16x32_bf16 v[56:59], v[166:169], v[210:213], v[56:59]
	v_mfma_f32_16x16x32_bf16 v[44:47], v[144:147], v[214:217], v[44:47]
	v_mfma_f32_16x16x32_bf16 v[44:47], v[148:151], v[218:221], v[44:47]
	v_mfma_f32_16x16x32_bf16 v[40:43], v[152:155], v[214:217], v[40:43]
	v_mfma_f32_16x16x32_bf16 v[40:43], v[166:169], v[218:221], v[40:43]
	v_mfma_f32_16x16x32_bf16 v[28:31], v[144:147], v[222:225], v[28:31]
	v_mfma_f32_16x16x32_bf16 v[28:31], v[148:151], v[226:229], v[28:31]
	v_mfma_f32_16x16x32_bf16 v[24:27], v[152:155], v[222:225], v[24:27]
	v_mfma_f32_16x16x32_bf16 v[24:27], v[166:169], v[226:229], v[24:27]
	v_mfma_f32_16x16x32_bf16 v[12:15], v[144:147], v[230:233], v[12:15]
	v_mfma_f32_16x16x32_bf16 v[12:15], v[148:151], v[234:237], v[12:15]
	v_mfma_f32_16x16x32_bf16 v[8:11], v[152:155], v[230:233], v[8:11]
	v_mfma_f32_16x16x32_bf16 v[8:11], v[166:169], v[234:237], v[8:11]
	v_mfma_f32_16x16x32_bf16 v[52:55], v[184:187], v[200:203], v[52:55]
	v_mfma_f32_16x16x32_bf16 v[52:55], v[188:191], v[210:213], v[52:55]
	v_mfma_f32_16x16x32_bf16 v[48:51], v[192:195], v[200:203], v[48:51]
	v_mfma_f32_16x16x32_bf16 v[48:51], v[196:199], v[210:213], v[48:51]
	v_mfma_f32_16x16x32_bf16 v[36:39], v[184:187], v[214:217], v[36:39]
	v_mfma_f32_16x16x32_bf16 v[36:39], v[188:191], v[218:221], v[36:39]
	v_mfma_f32_16x16x32_bf16 v[32:35], v[192:195], v[214:217], v[32:35]
	v_mfma_f32_16x16x32_bf16 v[32:35], v[196:199], v[218:221], v[32:35]
	v_mfma_f32_16x16x32_bf16 v[20:23], v[184:187], v[222:225], v[20:23]
	v_mfma_f32_16x16x32_bf16 v[20:23], v[188:191], v[226:229], v[20:23]
	v_mfma_f32_16x16x32_bf16 v[16:19], v[192:195], v[222:225], v[16:19]
	v_mfma_f32_16x16x32_bf16 v[16:19], v[196:199], v[226:229], v[16:19]
	v_mfma_f32_16x16x32_bf16 v[4:7], v[184:187], v[230:233], v[4:7]
	v_mfma_f32_16x16x32_bf16 v[4:7], v[188:191], v[234:237], v[4:7]
	s_setprio 3
	s_barrier
	v_mfma_f32_16x16x32_bf16 v[0:3], v[192:195], v[230:233], v[0:3]
	v_mfma_f32_16x16x32_bf16 v[0:3], v[196:199], v[234:237], v[0:3]
	s_setprio 0
	s_add_i32 s12, s12, 2
	s_add_u32 vcc_lo, vcc_lo, 0x100
	s_addc_u32 vcc_hi, vcc_hi, 0
	s_add_u32 s8, s8, 0x100
	s_addc_u32 s9, s9, 0
	s_cmp_gt_u32 s12, 13
	s_cbranch_scc1 .Lexit_242
.LBB0_242:
	s_add_u32 s2, s8, 0xfffc0080
	s_addc_u32 s3, s9, -1
	s_add_i32 s13, 0, 0x10000
	s_cmp_eq_u32 s12, 12
	s_cselect_b32 s53, s7, s3
	s_cselect_b32 s52, s35, s2
	v_add_u32_e32 v156, s13, v164
	s_cselect_b32 s11, s31, vcc_hi
	s_cselect_b32 s10, s89, vcc_lo
	s_add_i32 s77, 0, 0x14000
	ds_read_b128 v[144:147], v156
	ds_read_b128 v[148:151], v156 offset:1024
	ds_read_b128 v[152:155], v156 offset:2048
	ds_read_b128 v[166:169], v156 offset:3072
	v_add_u32_e32 v156, s77, v164
	ds_read_b128 v[184:187], v156
	ds_read_b128 v[188:191], v156 offset:1024
	ds_read_b128 v[192:195], v156 offset:2048
	ds_read_b128 v[196:199], v156 offset:3072
	v_lshl_add_u64 v[156:157], s[8:9], 0, v[142:143]
	s_add_i32 m0, s19, 0xc000
	ds_read_b128 v[200:203], v165
	ds_read_b128 v[210:213], v165 offset:1024
	ds_read_b128 v[214:217], v165 offset:2048
	ds_read_b128 v[218:221], v165 offset:3072
	ds_read_b128 v[222:225], v165 offset:4096
	ds_read_b128 v[226:229], v165 offset:5120
	ds_read_b128 v[230:233], v165 offset:6144
	ds_read_b128 v[234:237], v165 offset:7168
	global_load_lds_dwordx4 v[156:157], off
	v_lshl_add_u64 v[156:157], s[8:9], 0, v[140:141]
	s_add_i32 m0, s19, 0xe000
	s_nop 0
	global_load_lds_dwordx4 v[156:157], off
	s_waitcnt vmcnt(8)
	s_waitcnt lgkmcnt(0)
	s_setprio 1
	s_barrier
	v_mfma_f32_16x16x32_bf16 v[124:127], v[144:147], v[200:203], v[124:127]
	v_mfma_f32_16x16x32_bf16 v[124:127], v[148:151], v[210:213], v[124:127]
	v_mfma_f32_16x16x32_bf16 v[120:123], v[152:155], v[200:203], v[120:123]
	v_mfma_f32_16x16x32_bf16 v[120:123], v[166:169], v[210:213], v[120:123]
	v_mfma_f32_16x16x32_bf16 v[108:111], v[144:147], v[214:217], v[108:111]
	v_mfma_f32_16x16x32_bf16 v[108:111], v[148:151], v[218:221], v[108:111]
	v_mfma_f32_16x16x32_bf16 v[104:107], v[152:155], v[214:217], v[104:107]
	v_mfma_f32_16x16x32_bf16 v[104:107], v[166:169], v[218:221], v[104:107]
	v_mfma_f32_16x16x32_bf16 v[92:95], v[144:147], v[222:225], v[92:95]
	v_mfma_f32_16x16x32_bf16 v[92:95], v[148:151], v[226:229], v[92:95]
	v_mfma_f32_16x16x32_bf16 v[88:91], v[152:155], v[222:225], v[88:91]
	v_mfma_f32_16x16x32_bf16 v[88:91], v[166:169], v[226:229], v[88:91]
	v_mfma_f32_16x16x32_bf16 v[76:79], v[144:147], v[230:233], v[76:79]
	v_mfma_f32_16x16x32_bf16 v[76:79], v[148:151], v[234:237], v[76:79]
	v_mfma_f32_16x16x32_bf16 v[72:75], v[152:155], v[230:233], v[72:75]
	v_mfma_f32_16x16x32_bf16 v[72:75], v[166:169], v[234:237], v[72:75]
	v_mfma_f32_16x16x32_bf16 v[116:119], v[184:187], v[200:203], v[116:119]
	v_mfma_f32_16x16x32_bf16 v[116:119], v[188:191], v[210:213], v[116:119]
	v_mfma_f32_16x16x32_bf16 v[112:115], v[192:195], v[200:203], v[112:115]
	v_mfma_f32_16x16x32_bf16 v[112:115], v[196:199], v[210:213], v[112:115]
	v_mfma_f32_16x16x32_bf16 v[100:103], v[184:187], v[214:217], v[100:103]
	v_mfma_f32_16x16x32_bf16 v[100:103], v[188:191], v[218:221], v[100:103]
	v_mfma_f32_16x16x32_bf16 v[96:99], v[192:195], v[214:217], v[96:99]
	v_mfma_f32_16x16x32_bf16 v[96:99], v[196:199], v[218:221], v[96:99]
	v_mfma_f32_16x16x32_bf16 v[84:87], v[184:187], v[222:225], v[84:87]
	v_mfma_f32_16x16x32_bf16 v[84:87], v[188:191], v[226:229], v[84:87]
	v_mfma_f32_16x16x32_bf16 v[80:83], v[192:195], v[222:225], v[80:83]
	v_mfma_f32_16x16x32_bf16 v[80:83], v[196:199], v[226:229], v[80:83]
	v_mfma_f32_16x16x32_bf16 v[68:71], v[184:187], v[230:233], v[68:71]
	v_mfma_f32_16x16x32_bf16 v[68:71], v[188:191], v[234:237], v[68:71]
	s_setprio 3
	s_barrier
	v_mfma_f32_16x16x32_bf16 v[64:67], v[192:195], v[230:233], v[64:67]
	v_mfma_f32_16x16x32_bf16 v[64:67], v[196:199], v[234:237], v[64:67]
	s_setprio 0
	s_add_i32 s2, s13, s56
	v_lshl_add_u64 v[156:157], s[10:11], 0, v[174:175]
	s_mov_b32 m0, s2
	ds_read_b128 v[200:203], v165 offset:16384
	ds_read_b128 v[210:213], v165 offset:17408
	ds_read_b128 v[214:217], v165 offset:18432
	ds_read_b128 v[218:221], v165 offset:19456
	ds_read_b128 v[222:225], v165 offset:20480
	ds_read_b128 v[226:229], v165 offset:21504
	ds_read_b128 v[230:233], v165 offset:22528
	ds_read_b128 v[234:237], v165 offset:23552
	global_load_lds_dwordx4 v[156:157], off
	s_add_i32 m0, s2, 0x2000
	s_add_u32 s2, s10, 0x40000
	v_lshl_add_u64 v[170:171], s[10:11], 0, v[132:133]
	s_addc_u32 s3, s11, 0
	s_add_i32 s13, s77, s56
	global_load_lds_dwordx4 v[170:171], off
	v_lshl_add_u64 v[238:239], s[2:3], 0, v[174:175]
	s_mov_b32 m0, s13
	v_lshl_add_u64 v[240:241], s[52:53], 0, v[130:131]
	global_load_lds_dwordx4 v[238:239], off
	v_lshl_add_u64 v[238:239], s[2:3], 0, v[132:133]
	s_add_i32 m0, s13, 0x2000
	s_nop 0
	global_load_lds_dwordx4 v[238:239], off
	v_lshl_add_u64 v[238:239], s[52:53], 0, v[128:129]
	s_mov_b32 m0, s19
	s_nop 0
	global_load_lds_dwordx4 v[238:239], off
	s_mov_b32 m0, s57
	s_nop 0
	global_load_lds_dwordx4 v[240:241], off
	s_waitcnt vmcnt(8)
	s_waitcnt lgkmcnt(0)
	s_setprio 1
	s_barrier
	v_mfma_f32_16x16x32_bf16 v[60:63], v[144:147], v[200:203], v[60:63]
	v_mfma_f32_16x16x32_bf16 v[60:63], v[148:151], v[210:213], v[60:63]
	v_mfma_f32_16x16x32_bf16 v[56:59], v[152:155], v[200:203], v[56:59]
	v_mfma_f32_16x16x32_bf16 v[56:59], v[166:169], v[210:213], v[56:59]
	v_mfma_f32_16x16x32_bf16 v[44:47], v[144:147], v[214:217], v[44:47]
	v_mfma_f32_16x16x32_bf16 v[44:47], v[148:151], v[218:221], v[44:47]
	v_mfma_f32_16x16x32_bf16 v[40:43], v[152:155], v[214:217], v[40:43]
	v_mfma_f32_16x16x32_bf16 v[40:43], v[166:169], v[218:221], v[40:43]
	v_mfma_f32_16x16x32_bf16 v[28:31], v[144:147], v[222:225], v[28:31]
	v_mfma_f32_16x16x32_bf16 v[28:31], v[148:151], v[226:229], v[28:31]
	v_mfma_f32_16x16x32_bf16 v[24:27], v[152:155], v[222:225], v[24:27]
	v_mfma_f32_16x16x32_bf16 v[24:27], v[166:169], v[226:229], v[24:27]
	v_mfma_f32_16x16x32_bf16 v[12:15], v[144:147], v[230:233], v[12:15]
	v_mfma_f32_16x16x32_bf16 v[12:15], v[148:151], v[234:237], v[12:15]
	v_mfma_f32_16x16x32_bf16 v[8:11], v[152:155], v[230:233], v[8:11]
	v_mfma_f32_16x16x32_bf16 v[8:11], v[166:169], v[234:237], v[8:11]
	v_mfma_f32_16x16x32_bf16 v[52:55], v[184:187], v[200:203], v[52:55]
	v_mfma_f32_16x16x32_bf16 v[52:55], v[188:191], v[210:213], v[52:55]
	v_mfma_f32_16x16x32_bf16 v[48:51], v[192:195], v[200:203], v[48:51]
	v_mfma_f32_16x16x32_bf16 v[48:51], v[196:199], v[210:213], v[48:51]
	v_mfma_f32_16x16x32_bf16 v[36:39], v[184:187], v[214:217], v[36:39]
	v_mfma_f32_16x16x32_bf16 v[36:39], v[188:191], v[218:221], v[36:39]
	v_mfma_f32_16x16x32_bf16 v[32:35], v[192:195], v[214:217], v[32:35]
	v_mfma_f32_16x16x32_bf16 v[32:35], v[196:199], v[218:221], v[32:35]
	v_mfma_f32_16x16x32_bf16 v[20:23], v[184:187], v[222:225], v[20:23]
	v_mfma_f32_16x16x32_bf16 v[20:23], v[188:191], v[226:229], v[20:23]
	v_mfma_f32_16x16x32_bf16 v[16:19], v[192:195], v[222:225], v[16:19]
	v_mfma_f32_16x16x32_bf16 v[16:19], v[196:199], v[226:229], v[16:19]
	v_mfma_f32_16x16x32_bf16 v[4:7], v[184:187], v[230:233], v[4:7]
	v_mfma_f32_16x16x32_bf16 v[4:7], v[188:191], v[234:237], v[4:7]
	s_setprio 3
	s_barrier
	v_mfma_f32_16x16x32_bf16 v[0:3], v[192:195], v[230:233], v[0:3]
	v_mfma_f32_16x16x32_bf16 v[0:3], v[196:199], v[234:237], v[0:3]
	s_setprio 0
	s_add_i32 s13, 0, 0x18000
	s_add_i32 s77, 0, 0x1c000
	v_add_u32_e32 v166, s13, v164
	v_add_u32_e32 v183, s77, v164
	ds_read_b128 v[144:147], v166
	ds_read_b128 v[148:151], v166 offset:1024
	ds_read_b128 v[152:155], v166 offset:2048
	ds_read_b128 v[166:169], v166 offset:3072
	ds_read_b128 v[184:187], v183
	ds_read_b128 v[188:191], v183 offset:1024
	ds_read_b128 v[192:195], v183 offset:2048
	ds_read_b128 v[196:199], v183 offset:3072
	s_add_u32 s2, s52, 0x40000
	s_addc_u32 s3, s53, 0
	s_mov_b32 m0, s60
	v_lshl_add_u64 v[242:243], s[2:3], 0, v[128:129]
	ds_read_b128 v[200:203], v165 offset:32768
	ds_read_b128 v[210:213], v165 offset:33792
	ds_read_b128 v[214:217], v165 offset:34816
	ds_read_b128 v[218:221], v165 offset:35840
	ds_read_b128 v[222:225], v165 offset:36864
	ds_read_b128 v[226:229], v165 offset:37888
	ds_read_b128 v[230:233], v165 offset:38912
	ds_read_b128 v[234:237], v165 offset:39936
	global_load_lds_dwordx4 v[242:243], off
	v_lshl_add_u64 v[242:243], s[2:3], 0, v[130:131]
	s_mov_b32 m0, s61
	s_nop 0
	global_load_lds_dwordx4 v[242:243], off
	s_waitcnt vmcnt(8)
	s_waitcnt lgkmcnt(0)
	s_setprio 1
	s_barrier
	v_mfma_f32_16x16x32_bf16 v[124:127], v[144:147], v[200:203], v[124:127]
	v_mfma_f32_16x16x32_bf16 v[124:127], v[148:151], v[210:213], v[124:127]
	v_mfma_f32_16x16x32_bf16 v[120:123], v[152:155], v[200:203], v[120:123]
	v_mfma_f32_16x16x32_bf16 v[120:123], v[166:169], v[210:213], v[120:123]
	v_mfma_f32_16x16x32_bf16 v[108:111], v[144:147], v[214:217], v[108:111]
	v_mfma_f32_16x16x32_bf16 v[108:111], v[148:151], v[218:221], v[108:111]
	v_mfma_f32_16x16x32_bf16 v[104:107], v[152:155], v[214:217], v[104:107]
	v_mfma_f32_16x16x32_bf16 v[104:107], v[166:169], v[218:221], v[104:107]
	v_mfma_f32_16x16x32_bf16 v[92:95], v[144:147], v[222:225], v[92:95]
	v_mfma_f32_16x16x32_bf16 v[92:95], v[148:151], v[226:229], v[92:95]
	v_mfma_f32_16x16x32_bf16 v[88:91], v[152:155], v[222:225], v[88:91]
	v_mfma_f32_16x16x32_bf16 v[88:91], v[166:169], v[226:229], v[88:91]
	v_mfma_f32_16x16x32_bf16 v[76:79], v[144:147], v[230:233], v[76:79]
	v_mfma_f32_16x16x32_bf16 v[76:79], v[148:151], v[234:237], v[76:79]
	v_mfma_f32_16x16x32_bf16 v[72:75], v[152:155], v[230:233], v[72:75]
	v_mfma_f32_16x16x32_bf16 v[72:75], v[166:169], v[234:237], v[72:75]
	v_mfma_f32_16x16x32_bf16 v[116:119], v[184:187], v[200:203], v[116:119]
	v_mfma_f32_16x16x32_bf16 v[116:119], v[188:191], v[210:213], v[116:119]
	v_mfma_f32_16x16x32_bf16 v[112:115], v[192:195], v[200:203], v[112:115]
	v_mfma_f32_16x16x32_bf16 v[112:115], v[196:199], v[210:213], v[112:115]
	v_mfma_f32_16x16x32_bf16 v[100:103], v[184:187], v[214:217], v[100:103]
	v_mfma_f32_16x16x32_bf16 v[100:103], v[188:191], v[218:221], v[100:103]
	v_mfma_f32_16x16x32_bf16 v[96:99], v[192:195], v[214:217], v[96:99]
	v_mfma_f32_16x16x32_bf16 v[96:99], v[196:199], v[218:221], v[96:99]
	v_mfma_f32_16x16x32_bf16 v[84:87], v[184:187], v[222:225], v[84:87]
	v_mfma_f32_16x16x32_bf16 v[84:87], v[188:191], v[226:229], v[84:87]
	v_mfma_f32_16x16x32_bf16 v[80:83], v[192:195], v[222:225], v[80:83]
	v_mfma_f32_16x16x32_bf16 v[80:83], v[196:199], v[226:229], v[80:83]
	v_mfma_f32_16x16x32_bf16 v[68:71], v[184:187], v[230:233], v[68:71]
	v_mfma_f32_16x16x32_bf16 v[68:71], v[188:191], v[234:237], v[68:71]
	s_setprio 3
	s_barrier
	v_mfma_f32_16x16x32_bf16 v[64:67], v[192:195], v[230:233], v[64:67]
	v_mfma_f32_16x16x32_bf16 v[64:67], v[196:199], v[234:237], v[64:67]
	s_setprio 0
	s_add_i32 s2, s13, s56
	v_lshl_add_u64 v[156:157], v[156:157], 0, s[82:83]
	s_mov_b32 m0, s2
	ds_read_b128 v[200:203], v165 offset:49152
	ds_read_b128 v[210:213], v165 offset:50176
	ds_read_b128 v[214:217], v165 offset:51200
	ds_read_b128 v[218:221], v165 offset:52224
	ds_read_b128 v[222:225], v165 offset:53248
	ds_read_b128 v[226:229], v165 offset:54272
	ds_read_b128 v[230:233], v165 offset:55296
	ds_read_b128 v[234:237], v165 offset:56320
	global_load_lds_dwordx4 v[156:157], off
	s_add_i32 m0, s2, 0x2000
	s_add_u32 s2, s10, 0x40080
	v_lshl_add_u64 v[156:157], v[170:171], 0, s[82:83]
	s_addc_u32 s3, s11, 0
	s_add_i32 s10, s77, s56
	global_load_lds_dwordx4 v[156:157], off
	v_lshl_add_u64 v[156:157], s[2:3], 0, v[174:175]
	s_mov_b32 m0, s10
	s_nop 0
	global_load_lds_dwordx4 v[156:157], off
	v_lshl_add_u64 v[156:157], s[2:3], 0, v[132:133]
	s_add_i32 m0, s10, 0x2000
	s_nop 0
	global_load_lds_dwordx4 v[156:157], off
	v_lshl_add_u64 v[156:157], v[238:239], 0, s[82:83]
	s_mov_b32 m0, s39
	s_nop 0
	global_load_lds_dwordx4 v[156:157], off
	v_lshl_add_u64 v[156:157], v[240:241], 0, s[82:83]
	s_mov_b32 m0, s46
	s_nop 0
	global_load_lds_dwordx4 v[156:157], off
	s_waitcnt vmcnt(8)
	s_waitcnt lgkmcnt(0)
	s_setprio 1
	s_barrier
	v_mfma_f32_16x16x32_bf16 v[60:63], v[144:147], v[200:203], v[60:63]
	v_mfma_f32_16x16x32_bf16 v[60:63], v[148:151], v[210:213], v[60:63]
	v_mfma_f32_16x16x32_bf16 v[56:59], v[152:155], v[200:203], v[56:59]
	v_mfma_f32_16x16x32_bf16 v[56:59], v[166:169], v[210:213], v[56:59]
	v_mfma_f32_16x16x32_bf16 v[44:47], v[144:147], v[214:217], v[44:47]
	v_mfma_f32_16x16x32_bf16 v[44:47], v[148:151], v[218:221], v[44:47]
	v_mfma_f32_16x16x32_bf16 v[40:43], v[152:155], v[214:217], v[40:43]
	v_mfma_f32_16x16x32_bf16 v[40:43], v[166:169], v[218:221], v[40:43]
	v_mfma_f32_16x16x32_bf16 v[28:31], v[144:147], v[222:225], v[28:31]
	v_mfma_f32_16x16x32_bf16 v[28:31], v[148:151], v[226:229], v[28:31]
	v_mfma_f32_16x16x32_bf16 v[24:27], v[152:155], v[222:225], v[24:27]
	v_mfma_f32_16x16x32_bf16 v[24:27], v[166:169], v[226:229], v[24:27]
	v_mfma_f32_16x16x32_bf16 v[12:15], v[144:147], v[230:233], v[12:15]
	v_mfma_f32_16x16x32_bf16 v[12:15], v[148:151], v[234:237], v[12:15]
	v_mfma_f32_16x16x32_bf16 v[8:11], v[152:155], v[230:233], v[8:11]
	v_mfma_f32_16x16x32_bf16 v[8:11], v[166:169], v[234:237], v[8:11]
	v_mfma_f32_16x16x32_bf16 v[52:55], v[184:187], v[200:203], v[52:55]
	v_mfma_f32_16x16x32_bf16 v[52:55], v[188:191], v[210:213], v[52:55]
	v_mfma_f32_16x16x32_bf16 v[48:51], v[192:195], v[200:203], v[48:51]
	v_mfma_f32_16x16x32_bf16 v[48:51], v[196:199], v[210:213], v[48:51]
	v_mfma_f32_16x16x32_bf16 v[36:39], v[184:187], v[214:217], v[36:39]
	v_mfma_f32_16x16x32_bf16 v[36:39], v[188:191], v[218:221], v[36:39]
	v_mfma_f32_16x16x32_bf16 v[32:35], v[192:195], v[214:217], v[32:35]
	v_mfma_f32_16x16x32_bf16 v[32:35], v[196:199], v[218:221], v[32:35]
	v_mfma_f32_16x16x32_bf16 v[20:23], v[184:187], v[222:225], v[20:23]
	v_mfma_f32_16x16x32_bf16 v[20:23], v[188:191], v[226:229], v[20:23]
	v_mfma_f32_16x16x32_bf16 v[16:19], v[192:195], v[222:225], v[16:19]
	v_mfma_f32_16x16x32_bf16 v[16:19], v[196:199], v[226:229], v[16:19]
	v_mfma_f32_16x16x32_bf16 v[4:7], v[184:187], v[230:233], v[4:7]
	v_mfma_f32_16x16x32_bf16 v[4:7], v[188:191], v[234:237], v[4:7]
	s_setprio 3
	s_barrier
	v_mfma_f32_16x16x32_bf16 v[0:3], v[192:195], v[230:233], v[0:3]
	v_mfma_f32_16x16x32_bf16 v[0:3], v[196:199], v[234:237], v[0:3]
	s_setprio 0
	s_add_i32 s12, s12, 2
	s_add_u32 vcc_lo, vcc_lo, 0x100
	s_addc_u32 vcc_hi, vcc_hi, 0
	s_add_u32 s8, s8, 0x100
	s_addc_u32 s9, s9, 0
	s_cmp_gt_u32 s12, 13
	s_cbranch_scc0 .LBB0_242
